# gate/up GEMM epilogue: silu through v_rcp_f32 and a multiply instead of the full IEEE division sequence (f32)
# speedup vs baseline: 1.2616x; 1.0078x over previous
.LBB0_1497:
	v_mul_f32_e32 v144, 0xbfb8aa3b, v126
	v_mul_f32_e32 v145, 0xbfb8aa3b, v127
	v_exp_f32_e32 v144, v144
	v_exp_f32_e32 v145, v145
	v_lshl_or_b32 v148, s48, 7, v153
	v_lshl_add_u32 v155, s24, 8, v143
	v_ashrrev_i32_e32 v149, 31, v148
	v_pk_add_f32 v[144:145], v[144:145], 1.0 op_sel_hi:[1,0]
	v_mov_b64_e32 v[140:141], s[12:13]
	s_movk_i32 s2, 0x1600
	v_mad_i64_i32 v[150:151], s[0:1], v155, s2, v[140:141]
	v_rcp_f32_e32 v146, v145
	s_nop 0
	v_mul_f32_e32 v127, v127, v146
	v_rcp_f32_e32 v145, v144
	s_nop 0
	v_mul_f32_e32 v126, v126, v145
	v_pk_mul_f32 v[122:123], v[126:127], v[122:123]
	v_mul_f32_e32 v126, 0xbfb8aa3b, v128
	v_mul_f32_e32 v127, 0xbfb8aa3b, v129
	v_exp_f32_e32 v126, v126
	v_exp_f32_e32 v127, v127
	s_nop 0
	v_pk_add_f32 v[126:127], v[126:127], 1.0 op_sel_hi:[1,0]
	s_nop 0
	v_rcp_f32_e32 v144, v127
	s_nop 0
	v_mul_f32_e32 v127, v129, v144
	v_rcp_f32_e32 v129, v126
	s_nop 0
	v_mul_f32_e32 v126, v128, v129
	v_pk_mul_f32 v[124:125], v[126:127], v[124:125]
	v_mul_f32_e32 v126, 0xbfb8aa3b, v118
	v_mul_f32_e32 v127, 0xbfb8aa3b, v119
	v_exp_f32_e32 v126, v126
	v_exp_f32_e32 v127, v127
	s_nop 0
	v_pk_add_f32 v[126:127], v[126:127], 1.0 op_sel_hi:[1,0]
	s_nop 0
	v_rcp_f32_e32 v128, v127
	s_nop 0
	v_mul_f32_e32 v119, v119, v128
	v_rcp_f32_e32 v127, v126
	s_nop 0
	v_mul_f32_e32 v118, v118, v127
	v_pk_mul_f32 v[118:119], v[118:119], v[114:115]
	v_mul_f32_e32 v114, 0xbfb8aa3b, v120
	v_mul_f32_e32 v115, 0xbfb8aa3b, v121
	v_exp_f32_e32 v114, v114
	v_exp_f32_e32 v115, v115
	v_cvt_pk_bf16_f32 v118, v118, v119
	v_pk_add_f32 v[114:115], v[114:115], 1.0 op_sel_hi:[1,0]
	s_nop 0
	v_rcp_f32_e32 v126, v115
	s_nop 0
	v_mul_f32_e32 v115, v121, v126
	v_rcp_f32_e32 v121, v114
	s_nop 0
	v_mul_f32_e32 v114, v120, v121
	v_pk_mul_f32 v[120:121], v[114:115], v[116:117]
	v_lshlrev_b64 v[114:115], 1, v[148:149]
	v_lshl_add_u64 v[126:127], v[150:151], 0, v[114:115]
	v_cvt_pk_bf16_f32 v116, v122, v123
	v_cvt_pk_bf16_f32 v117, v124, v125
	v_cvt_pk_bf16_f32 v119, v120, v121
	flat_store_dwordx4 v[126:127], v[116:119]
	s_nop 1
	v_mul_f32_e32 v118, 0xbfb8aa3b, v110
	v_mul_f32_e32 v119, 0xbfb8aa3b, v111
	v_exp_f32_e32 v118, v118
	v_exp_f32_e32 v119, v119
	v_or_b32_e32 v116, 16, v155
	v_mad_i64_i32 v[116:117], s[0:1], v116, s2, v[140:141]
	v_pk_add_f32 v[118:119], v[118:119], 1.0 op_sel_hi:[1,0]
	s_nop 0
	v_rcp_f32_e32 v120, v119
	s_nop 0
	v_mul_f32_e32 v111, v111, v120
	v_rcp_f32_e32 v119, v118
	s_nop 0
	v_mul_f32_e32 v110, v110, v119
	v_pk_mul_f32 v[106:107], v[110:111], v[106:107]
	v_mul_f32_e32 v110, 0xbfb8aa3b, v112
	v_mul_f32_e32 v111, 0xbfb8aa3b, v113
	v_exp_f32_e32 v110, v110
	v_exp_f32_e32 v111, v111
	s_nop 0
	v_pk_add_f32 v[110:111], v[110:111], 1.0 op_sel_hi:[1,0]
	s_nop 0
	v_rcp_f32_e32 v118, v111
	s_nop 0
	v_mul_f32_e32 v111, v113, v118
	v_rcp_f32_e32 v113, v110
	s_nop 0
	v_mul_f32_e32 v110, v112, v113
	v_pk_mul_f32 v[108:109], v[110:111], v[108:109]
	v_mul_f32_e32 v110, 0xbfb8aa3b, v102
	v_mul_f32_e32 v111, 0xbfb8aa3b, v103
	v_exp_f32_e32 v110, v110
	v_exp_f32_e32 v111, v111
	s_nop 0
	v_pk_add_f32 v[110:111], v[110:111], 1.0 op_sel_hi:[1,0]
	s_nop 0
	v_rcp_f32_e32 v112, v111
	s_nop 0
	v_mul_f32_e32 v103, v103, v112
	v_rcp_f32_e32 v111, v110
	s_nop 0
	v_mul_f32_e32 v102, v102, v111
	v_pk_mul_f32 v[102:103], v[102:103], v[98:99]
	v_mul_f32_e32 v98, 0xbfb8aa3b, v104
	v_mul_f32_e32 v99, 0xbfb8aa3b, v105
	v_exp_f32_e32 v98, v98
	v_exp_f32_e32 v99, v99
	s_nop 0
	v_pk_add_f32 v[98:99], v[98:99], 1.0 op_sel_hi:[1,0]
	s_nop 0
	v_rcp_f32_e32 v110, v99
	s_nop 0
	v_mul_f32_e32 v99, v105, v110
	v_rcp_f32_e32 v105, v98
	s_nop 0
	v_mul_f32_e32 v98, v104, v105
	v_pk_mul_f32 v[104:105], v[98:99], v[100:101]
	v_lshl_add_u64 v[110:111], v[116:117], 0, v[114:115]
	v_cvt_pk_bf16_f32 v98, v106, v107
	v_cvt_pk_bf16_f32 v99, v108, v109
	v_cvt_pk_bf16_f32 v100, v102, v103
	v_cvt_pk_bf16_f32 v101, v104, v105
	flat_store_dwordx4 v[110:111], v[98:101]
	s_nop 1
	v_mul_f32_e32 v100, 0xbfb8aa3b, v94
	v_mul_f32_e32 v101, 0xbfb8aa3b, v95
	v_exp_f32_e32 v100, v100
	v_exp_f32_e32 v101, v101
	v_or_b32_e32 v98, 32, v155
	v_mad_i64_i32 v[98:99], s[0:1], v98, s2, v[140:141]
	v_pk_add_f32 v[100:101], v[100:101], 1.0 op_sel_hi:[1,0]
	s_nop 0
	v_rcp_f32_e32 v102, v101
	s_nop 0
	v_mul_f32_e32 v95, v95, v102
	v_rcp_f32_e32 v101, v100
	s_nop 0
	v_mul_f32_e32 v94, v94, v101
	v_pk_mul_f32 v[90:91], v[94:95], v[90:91]
	v_mul_f32_e32 v94, 0xbfb8aa3b, v96
	v_mul_f32_e32 v95, 0xbfb8aa3b, v97
	v_exp_f32_e32 v94, v94
	v_exp_f32_e32 v95, v95
	s_nop 0
	v_pk_add_f32 v[94:95], v[94:95], 1.0 op_sel_hi:[1,0]
	s_nop 0
	v_rcp_f32_e32 v100, v95
	s_nop 0
	v_mul_f32_e32 v95, v97, v100
	v_rcp_f32_e32 v97, v94
	s_nop 0
	v_mul_f32_e32 v94, v96, v97
	v_pk_mul_f32 v[92:93], v[94:95], v[92:93]
	v_mul_f32_e32 v94, 0xbfb8aa3b, v86
	v_mul_f32_e32 v95, 0xbfb8aa3b, v87
	v_exp_f32_e32 v94, v94
	v_exp_f32_e32 v95, v95
	s_nop 0
	v_pk_add_f32 v[94:95], v[94:95], 1.0 op_sel_hi:[1,0]
	s_nop 0
	v_rcp_f32_e32 v96, v95
	s_nop 0
	v_mul_f32_e32 v87, v87, v96
	v_rcp_f32_e32 v95, v94
	s_nop 0
	v_mul_f32_e32 v86, v86, v95
	v_pk_mul_f32 v[86:87], v[86:87], v[82:83]
	v_mul_f32_e32 v82, 0xbfb8aa3b, v88
	v_mul_f32_e32 v83, 0xbfb8aa3b, v89
	v_exp_f32_e32 v82, v82
	v_exp_f32_e32 v83, v83
	s_nop 0
	v_pk_add_f32 v[82:83], v[82:83], 1.0 op_sel_hi:[1,0]
	s_nop 0
	v_rcp_f32_e32 v94, v83
	s_nop 0
	v_mul_f32_e32 v83, v89, v94
	v_rcp_f32_e32 v89, v82
	s_nop 0
	v_mul_f32_e32 v82, v88, v89
	v_pk_mul_f32 v[88:89], v[82:83], v[84:85]
	v_lshl_add_u64 v[94:95], v[98:99], 0, v[114:115]
	v_cvt_pk_bf16_f32 v82, v90, v91
	v_cvt_pk_bf16_f32 v83, v92, v93
	v_cvt_pk_bf16_f32 v84, v86, v87
	v_cvt_pk_bf16_f32 v85, v88, v89
	flat_store_dwordx4 v[94:95], v[82:85]
	s_nop 1
	v_mul_f32_e32 v84, 0xbfb8aa3b, v78
	v_mul_f32_e32 v85, 0xbfb8aa3b, v79
	v_exp_f32_e32 v84, v84
	v_exp_f32_e32 v85, v85
	v_or_b32_e32 v82, 48, v155
	v_mad_i64_i32 v[82:83], s[0:1], v82, s2, v[140:141]
	v_pk_add_f32 v[84:85], v[84:85], 1.0 op_sel_hi:[1,0]
	s_nop 0
	v_rcp_f32_e32 v86, v85
	s_nop 0
	v_mul_f32_e32 v79, v79, v86
	v_rcp_f32_e32 v85, v84
	s_nop 0
	v_mul_f32_e32 v78, v78, v85
	v_pk_mul_f32 v[74:75], v[78:79], v[74:75]
	v_mul_f32_e32 v78, 0xbfb8aa3b, v80
	v_mul_f32_e32 v79, 0xbfb8aa3b, v81
	v_exp_f32_e32 v78, v78
	v_exp_f32_e32 v79, v79
	s_nop 0
	v_pk_add_f32 v[78:79], v[78:79], 1.0 op_sel_hi:[1,0]
	s_nop 0
	v_rcp_f32_e32 v84, v79
	s_nop 0
	v_mul_f32_e32 v79, v81, v84
	v_rcp_f32_e32 v81, v78
	s_nop 0
	v_mul_f32_e32 v78, v80, v81
	v_pk_mul_f32 v[76:77], v[78:79], v[76:77]
	v_mul_f32_e32 v78, 0xbfb8aa3b, v70
	v_mul_f32_e32 v79, 0xbfb8aa3b, v71
	v_exp_f32_e32 v78, v78
	v_exp_f32_e32 v79, v79
	s_nop 0
	v_pk_add_f32 v[78:79], v[78:79], 1.0 op_sel_hi:[1,0]
	s_nop 0
	v_rcp_f32_e32 v80, v79
	s_nop 0
	v_mul_f32_e32 v71, v71, v80
	v_rcp_f32_e32 v79, v78
	s_nop 0
	v_mul_f32_e32 v70, v70, v79
	v_pk_mul_f32 v[70:71], v[70:71], v[66:67]
	v_mul_f32_e32 v66, 0xbfb8aa3b, v72
	v_mul_f32_e32 v67, 0xbfb8aa3b, v73
	v_exp_f32_e32 v66, v66
	v_exp_f32_e32 v67, v67
	s_nop 0
	v_pk_add_f32 v[66:67], v[66:67], 1.0 op_sel_hi:[1,0]
	s_nop 0
	v_rcp_f32_e32 v78, v67
	s_nop 0
	v_mul_f32_e32 v67, v73, v78
	v_rcp_f32_e32 v73, v66
	s_nop 0
	v_mul_f32_e32 v66, v72, v73
	v_pk_mul_f32 v[72:73], v[66:67], v[68:69]
	v_lshl_add_u64 v[78:79], v[82:83], 0, v[114:115]
	v_cvt_pk_bf16_f32 v66, v74, v75
	v_cvt_pk_bf16_f32 v67, v76, v77
	v_cvt_pk_bf16_f32 v68, v70, v71
	v_cvt_pk_bf16_f32 v69, v72, v73
	flat_store_dwordx4 v[78:79], v[66:69]
	s_nop 1
	v_mul_f32_e32 v68, 0xbfb8aa3b, v60
	v_mul_f32_e32 v69, 0xbfb8aa3b, v61
	v_exp_f32_e32 v68, v68
	v_exp_f32_e32 v69, v69
	v_add_u32_e32 v66, 0x80, v155
	v_mad_i64_i32 v[66:67], s[0:1], v66, s2, v[140:141]
	v_pk_add_f32 v[68:69], v[68:69], 1.0 op_sel_hi:[1,0]
	s_nop 0
	v_rcp_f32_e32 v70, v69
	s_nop 0
	v_mul_f32_e32 v61, v61, v70
	v_rcp_f32_e32 v69, v68
	s_nop 0
	v_mul_f32_e32 v60, v60, v69
	v_pk_mul_f32 v[56:57], v[60:61], v[56:57]
	v_mul_f32_e32 v60, 0xbfb8aa3b, v62
	v_mul_f32_e32 v61, 0xbfb8aa3b, v63
	v_exp_f32_e32 v60, v60
	v_exp_f32_e32 v61, v61
	s_nop 0
	v_pk_add_f32 v[60:61], v[60:61], 1.0 op_sel_hi:[1,0]
	s_nop 0
	v_rcp_f32_e32 v68, v61
	s_nop 0
	v_mul_f32_e32 v61, v63, v68
	v_rcp_f32_e32 v63, v60
	s_nop 0
	v_mul_f32_e32 v60, v62, v63
	v_pk_mul_f32 v[58:59], v[60:61], v[58:59]
	v_mul_f32_e32 v60, 0xbfb8aa3b, v52
	v_mul_f32_e32 v61, 0xbfb8aa3b, v53
	v_exp_f32_e32 v60, v60
	v_exp_f32_e32 v61, v61
	s_nop 0
	v_pk_add_f32 v[60:61], v[60:61], 1.0 op_sel_hi:[1,0]
	s_nop 0
	v_rcp_f32_e32 v62, v61
	s_nop 0
	v_mul_f32_e32 v53, v53, v62
	v_rcp_f32_e32 v61, v60
	s_nop 0
	v_mul_f32_e32 v52, v52, v61
	v_pk_mul_f32 v[52:53], v[52:53], v[48:49]
	v_mul_f32_e32 v48, 0xbfb8aa3b, v54
	v_mul_f32_e32 v49, 0xbfb8aa3b, v55
	v_exp_f32_e32 v48, v48
	v_exp_f32_e32 v49, v49
	s_nop 0
	v_pk_add_f32 v[48:49], v[48:49], 1.0 op_sel_hi:[1,0]
	s_nop 0
	v_rcp_f32_e32 v60, v49
	s_nop 0
	v_mul_f32_e32 v49, v55, v60
	v_rcp_f32_e32 v55, v48
	s_nop 0
	v_mul_f32_e32 v48, v54, v55
	v_pk_mul_f32 v[54:55], v[48:49], v[50:51]
	v_lshl_add_u64 v[60:61], v[66:67], 0, v[114:115]
	v_cvt_pk_bf16_f32 v48, v56, v57
	v_cvt_pk_bf16_f32 v49, v58, v59
	v_cvt_pk_bf16_f32 v50, v52, v53
	v_cvt_pk_bf16_f32 v51, v54, v55
	flat_store_dwordx4 v[60:61], v[48:51]
	s_nop 1
	v_mul_f32_e32 v50, 0xbfb8aa3b, v44
	v_mul_f32_e32 v51, 0xbfb8aa3b, v45
	v_exp_f32_e32 v50, v50
	v_exp_f32_e32 v51, v51
	v_add_u32_e32 v48, 0x90, v155
	v_mad_i64_i32 v[48:49], s[0:1], v48, s2, v[140:141]
	v_pk_add_f32 v[50:51], v[50:51], 1.0 op_sel_hi:[1,0]
	s_nop 0
	v_rcp_f32_e32 v52, v51
	s_nop 0
	v_mul_f32_e32 v45, v45, v52
	v_rcp_f32_e32 v51, v50
	s_nop 0
	v_mul_f32_e32 v44, v44, v51
	v_pk_mul_f32 v[40:41], v[44:45], v[40:41]
	v_mul_f32_e32 v44, 0xbfb8aa3b, v46
	v_mul_f32_e32 v45, 0xbfb8aa3b, v47
	v_exp_f32_e32 v44, v44
	v_exp_f32_e32 v45, v45
	s_nop 0
	v_pk_add_f32 v[44:45], v[44:45], 1.0 op_sel_hi:[1,0]
	s_nop 0
	v_rcp_f32_e32 v50, v45
	s_nop 0
	v_mul_f32_e32 v45, v47, v50
	v_rcp_f32_e32 v47, v44
	s_nop 0
	v_mul_f32_e32 v44, v46, v47
	v_pk_mul_f32 v[42:43], v[44:45], v[42:43]
	v_mul_f32_e32 v44, 0xbfb8aa3b, v36
	v_mul_f32_e32 v45, 0xbfb8aa3b, v37
	v_exp_f32_e32 v44, v44
	v_exp_f32_e32 v45, v45
	s_nop 0
	v_pk_add_f32 v[44:45], v[44:45], 1.0 op_sel_hi:[1,0]
	s_nop 0
	v_rcp_f32_e32 v46, v45
	s_nop 0
	v_mul_f32_e32 v37, v37, v46
	v_rcp_f32_e32 v45, v44
	s_nop 0
	v_mul_f32_e32 v36, v36, v45
	v_pk_mul_f32 v[36:37], v[36:37], v[32:33]
	v_mul_f32_e32 v32, 0xbfb8aa3b, v38
	v_mul_f32_e32 v33, 0xbfb8aa3b, v39
	v_exp_f32_e32 v32, v32
	v_exp_f32_e32 v33, v33
	s_nop 0
	v_pk_add_f32 v[32:33], v[32:33], 1.0 op_sel_hi:[1,0]
	s_nop 0
	v_rcp_f32_e32 v44, v33
	s_nop 0
	v_mul_f32_e32 v33, v39, v44
	v_rcp_f32_e32 v39, v32
	s_nop 0
	v_mul_f32_e32 v32, v38, v39
	v_pk_mul_f32 v[38:39], v[32:33], v[34:35]
	v_lshl_add_u64 v[44:45], v[48:49], 0, v[114:115]
	v_cvt_pk_bf16_f32 v32, v40, v41
	v_cvt_pk_bf16_f32 v33, v42, v43
	v_cvt_pk_bf16_f32 v34, v36, v37
	v_cvt_pk_bf16_f32 v35, v38, v39
	flat_store_dwordx4 v[44:45], v[32:35]
	s_nop 1
	v_mul_f32_e32 v34, 0xbfb8aa3b, v28
	v_mul_f32_e32 v35, 0xbfb8aa3b, v29
	v_exp_f32_e32 v34, v34
	v_exp_f32_e32 v35, v35
	v_add_u32_e32 v32, 0xa0, v155
	v_mad_i64_i32 v[32:33], s[0:1], v32, s2, v[140:141]
	v_pk_add_f32 v[34:35], v[34:35], 1.0 op_sel_hi:[1,0]
	s_nop 0
	v_rcp_f32_e32 v36, v35
	s_nop 0
	v_mul_f32_e32 v29, v29, v36
	v_rcp_f32_e32 v35, v34
	s_nop 0
	v_mul_f32_e32 v28, v28, v35
	v_pk_mul_f32 v[24:25], v[28:29], v[24:25]
	v_mul_f32_e32 v28, 0xbfb8aa3b, v30
	v_mul_f32_e32 v29, 0xbfb8aa3b, v31
	v_exp_f32_e32 v28, v28
	v_exp_f32_e32 v29, v29
	s_nop 0
	v_pk_add_f32 v[28:29], v[28:29], 1.0 op_sel_hi:[1,0]
	s_nop 0
	v_rcp_f32_e32 v34, v29
	s_nop 0
	v_mul_f32_e32 v29, v31, v34
	v_rcp_f32_e32 v31, v28
	s_nop 0
	v_mul_f32_e32 v28, v30, v31
	v_pk_mul_f32 v[26:27], v[28:29], v[26:27]
	v_mul_f32_e32 v28, 0xbfb8aa3b, v20
	v_mul_f32_e32 v29, 0xbfb8aa3b, v21
	v_exp_f32_e32 v28, v28
	v_exp_f32_e32 v29, v29
	s_nop 0
	v_pk_add_f32 v[28:29], v[28:29], 1.0 op_sel_hi:[1,0]
	s_nop 0
	v_rcp_f32_e32 v30, v29
	s_nop 0
	v_mul_f32_e32 v21, v21, v30
	v_rcp_f32_e32 v29, v28
	s_nop 0
	v_mul_f32_e32 v20, v20, v29
	v_pk_mul_f32 v[20:21], v[20:21], v[16:17]
	v_mul_f32_e32 v16, 0xbfb8aa3b, v22
	v_mul_f32_e32 v17, 0xbfb8aa3b, v23
	v_exp_f32_e32 v16, v16
	v_exp_f32_e32 v17, v17
	s_nop 0
	v_pk_add_f32 v[16:17], v[16:17], 1.0 op_sel_hi:[1,0]
	s_nop 0
	v_rcp_f32_e32 v28, v17
	s_nop 0
	v_mul_f32_e32 v17, v23, v28
	v_rcp_f32_e32 v23, v16
	s_nop 0
	v_mul_f32_e32 v16, v22, v23
	v_pk_mul_f32 v[22:23], v[16:17], v[18:19]
	v_lshl_add_u64 v[28:29], v[32:33], 0, v[114:115]
	v_cvt_pk_bf16_f32 v16, v24, v25
	v_cvt_pk_bf16_f32 v17, v26, v27
	v_cvt_pk_bf16_f32 v18, v20, v21
	v_cvt_pk_bf16_f32 v19, v22, v23
	flat_store_dwordx4 v[28:29], v[16:19]
	s_nop 1
	v_mul_f32_e32 v18, 0xbfb8aa3b, v12
	v_mul_f32_e32 v19, 0xbfb8aa3b, v13
	v_exp_f32_e32 v18, v18
	v_exp_f32_e32 v19, v19
	v_add_u32_e32 v16, 0xb0, v155
	v_mad_i64_i32 v[16:17], s[0:1], v16, s2, v[140:141]
	v_pk_add_f32 v[18:19], v[18:19], 1.0 op_sel_hi:[1,0]
	s_nop 0
	v_rcp_f32_e32 v20, v19
	s_nop 0
	v_mul_f32_e32 v13, v13, v20
	v_rcp_f32_e32 v19, v18
	s_nop 0
	v_mul_f32_e32 v12, v12, v19
	v_pk_mul_f32 v[8:9], v[12:13], v[8:9]
	v_mul_f32_e32 v12, 0xbfb8aa3b, v14
	v_mul_f32_e32 v13, 0xbfb8aa3b, v15
	v_exp_f32_e32 v12, v12
	v_exp_f32_e32 v13, v13
	s_nop 0
	v_pk_add_f32 v[12:13], v[12:13], 1.0 op_sel_hi:[1,0]
	s_nop 0
	v_rcp_f32_e32 v18, v13
	s_nop 0
	v_mul_f32_e32 v13, v15, v18
	v_rcp_f32_e32 v15, v12
	s_nop 0
	v_mul_f32_e32 v12, v14, v15
	v_pk_mul_f32 v[10:11], v[12:13], v[10:11]
	v_mul_f32_e32 v12, 0xbfb8aa3b, v4
	v_mul_f32_e32 v13, 0xbfb8aa3b, v5
	v_exp_f32_e32 v12, v12
	v_exp_f32_e32 v13, v13
	s_nop 0
	v_pk_add_f32 v[12:13], v[12:13], 1.0 op_sel_hi:[1,0]
	s_nop 0
	v_rcp_f32_e32 v14, v13
	s_nop 0
	v_mul_f32_e32 v5, v5, v14
	v_rcp_f32_e32 v13, v12
	s_nop 0
	v_mul_f32_e32 v4, v4, v13
	v_pk_mul_f32 v[4:5], v[4:5], v[0:1]
	v_mul_f32_e32 v0, 0xbfb8aa3b, v6
	v_mul_f32_e32 v1, 0xbfb8aa3b, v7
	v_exp_f32_e32 v0, v0
	v_exp_f32_e32 v1, v1
	s_nop 0
	v_pk_add_f32 v[0:1], v[0:1], 1.0 op_sel_hi:[1,0]
	s_nop 0
	v_rcp_f32_e32 v12, v1
	s_nop 0
	v_mul_f32_e32 v1, v7, v12
	s_mov_b64 s[0:1], -1
	v_rcp_f32_e32 v7, v0
	s_nop 0
	v_mul_f32_e32 v0, v6, v7
	v_pk_mul_f32 v[6:7], v[0:1], v[2:3]
	v_lshl_add_u64 v[12:13], v[16:17], 0, v[114:115]
	v_cvt_pk_bf16_f32 v0, v8, v9
	v_cvt_pk_bf16_f32 v1, v10, v11
	v_cvt_pk_bf16_f32 v2, v4, v5
	v_cvt_pk_bf16_f32 v3, v6, v7
	s_andn2_b64 vcc, exec, s[8:9]
	flat_store_dwordx4 v[12:13], v[0:3]
	s_cbranch_vccnz .LBB0_1490
	s_andn2_b64 vcc, exec, s[10:11]
	s_cbranch_vccnz .LBB0_1489
	s_barrier
	s_branch .LBB0_1489
